# grid barriers: the acquire's L1 invalidate (buffer_inv sc1) issued by wave 1 right after the opening s_barrier and waited for there, instead of by thread 0 after the release on every workgroup's criti
# speedup vs baseline: 1.0167x; 1.0167x over previous
; __device__ __forceinline__ void xcd_barrier(const XcdBarrier& b) {
;     asm volatile("s_waitcnt vmcnt(0)" ::: "memory");
;     __syncthreads();
;     if (threadIdx.x == 0) {
;         unsigned* bar = b.bar;
;         __builtin_amdgcn_s_waitcnt(0);
;         unsigned nloc = b.st[0], nx = b.st[1];
;         if (nloc == 0u) { xcd_barrier_complete(bar, b.x, nloc, nx); b.st[0] = nloc; b.st[1] = nx; }
.LBB0_1200:
	s_waitcnt vmcnt(0)
	s_waitcnt vmcnt(0)
	s_barrier
	v_readfirstlane_b32 s0, v174
	s_nop 3
	s_cmp_eq_u32 s0, 64
	s_cbranch_scc0 .Learlyinv0
	buffer_inv sc1
	s_waitcnt vmcnt(0)
.Learlyinv0:
	s_mov_b64 s[4:5], exec
	v_readlane_b32 s0, v251, 18
	v_readlane_b32 s1, v251, 19
	s_and_b64 s[0:1], s[4:5], s[0:1]
	s_mov_b64 exec, s[0:1]
	s_cbranch_execz .LBB0_1252
	v_readlane_b32 s0, v253, 46
	s_waitcnt vmcnt(0) expcnt(0) lgkmcnt(0)
	s_nop 0
	v_mov_b32_e32 v0, s0
	ds_read_b32 v2, v0
	v_readlane_b32 s0, v253, 47
	s_waitcnt lgkmcnt(0)
	v_cmp_ne_u32_e32 vcc, 0, v2
	v_mov_b32_e32 v0, s0
	ds_read_b32 v0, v0
	s_cbranch_vccnz .LBB0_1216
	s_mov_b32 s26, 1
	s_branch .LBB0_1204

; __device__ __forceinline__ unsigned xb_ld(unsigned* p)              { return __hip_atomic_load(p, __ATOMIC_RELAXED, __HIP_MEMORY_SCOPE_AGENT); }
; #define XB_SPIN(cond, bar) do { unsigned _sp = 0; while (cond) { __builtin_amdgcn_s_sleep(1); \
;     if ((++_sp & 255u) == 0u) { if (xb_ld(&(bar)[XB_TMO])) break; if (_sp > XB_SPIN_CAP) { atomicAdd(&(bar)[XB_TMO], 1u); break; } } } } while (0)
; __device__ __forceinline__ void xcd_barrier(const XcdBarrier& b) {
;     ...
;             XB_SPIN(xb_ld(&bar[XB_XGEN(b.x)]) == gen, bar);
;             __builtin_amdgcn_fence(__ATOMIC_ACQUIRE, "agent");
;             asm volatile("s_waitcnt vmcnt(0)" ::: "memory");
.LBB0_1231:
	s_or_b64 exec, exec, s[6:7]
	s_waitcnt vmcnt(0)
	s_waitcnt vmcnt(0)

; __device__ __forceinline__ unsigned xb_add(unsigned* p, unsigned v) { return __hip_atomic_fetch_add(p, v, __ATOMIC_RELAXED, __HIP_MEMORY_SCOPE_AGENT); }
; __device__ __forceinline__ void xcd_barrier(const XcdBarrier& b) {
;     ...
;             __builtin_amdgcn_fence(__ATOMIC_ACQUIRE, "agent");
;             xb_add(&bar[XB_XGEN(b.x)], 1u);
.LBB0_1249:
	s_or_b64 exec, exec, s[0:1]
	s_mov_b64 s[0:1], exec
	v_mbcnt_lo_u32_b32 v0, s0, 0
	v_mbcnt_hi_u32_b32 v0, s1, v0
	v_cmp_eq_u32_e32 vcc, 0, v0
	s_waitcnt vmcnt(0)
	s_and_saveexec_b64 s[6:7], vcc
	s_cbranch_execz .LBB0_1251
	s_bcnt1_i32_b64 s0, s[0:1]
	v_mov_b32_e32 v0, s0
	v_readlane_b32 s0, v252, 40
	v_readlane_b32 s1, v252, 41
	s_nop 4
	global_atomic_add v145, v0, s[0:1]

; __device__ __forceinline__ void xcd_barrier(const XcdBarrier& b) {
;     asm volatile("s_waitcnt vmcnt(0)" ::: "memory");
;     __syncthreads();
.LBB0_1253:
	s_waitcnt vmcnt(0)
	s_barrier
	v_readfirstlane_b32 s0, v174
	s_nop 3
	s_cmp_eq_u32 s0, 64
	s_cbranch_scc0 .Learlyinv1
	buffer_inv sc1
	s_waitcnt vmcnt(0)

; __device__ __forceinline__ void xcd_barrier(const XcdBarrier& b) {
;     asm volatile("s_waitcnt vmcnt(0)" ::: "memory");
;     __syncthreads();
.LBB0_1387:
	s_or_b64 exec, exec, s[4:5]
	s_waitcnt vmcnt(0)
	s_waitcnt vmcnt(63) expcnt(7) lgkmcnt(15)
	s_barrier
	v_readfirstlane_b32 s0, v174
	s_nop 3
	s_cmp_eq_u32 s0, 64
	s_cbranch_scc0 .Learlyinv2
	buffer_inv sc1
	s_waitcnt vmcnt(0)

; __device__ __forceinline__ void xcd_barrier(const XcdBarrier& b) {
;     asm volatile("s_waitcnt vmcnt(0)" ::: "memory");
;     __syncthreads();
.LBB0_1585:
	s_waitcnt vmcnt(0)
	s_waitcnt vmcnt(0) lgkmcnt(0)
	s_barrier
	v_readfirstlane_b32 s0, v174
	s_nop 3
	s_cmp_eq_u32 s0, 64
	s_cbranch_scc0 .Learlyinv4
	buffer_inv sc1
	s_waitcnt vmcnt(0)

; __device__ __forceinline__ void xcd_barrier(const XcdBarrier& b) {
;     ...
;     if (threadIdx.x == 0) {
;         unsigned* bar = b.bar;
;         __builtin_amdgcn_s_waitcnt(0);
;         unsigned nloc = b.st[0], nx = b.st[1];
;         if (nloc == 0u) { xcd_barrier_complete(bar, b.x, nloc, nx); b.st[0] = nloc; b.st[1] = nx; }
.Learlyinv6:
	s_mov_b64 s[4:5], exec
	v_readlane_b32 s0, v251, 18
	v_readlane_b32 s1, v251, 19
	s_and_b64 s[0:1], s[4:5], s[0:1]
	s_mov_b64 exec, s[0:1]
	s_cbranch_execnz .LBB0_1924
	s_getpc_b64 s[98:99]

; __device__ __forceinline__ unsigned xb_add(unsigned* p, unsigned v) { return __hip_atomic_fetch_add(p, v, __ATOMIC_RELAXED, __HIP_MEMORY_SCOPE_AGENT); }
; __device__ __forceinline__ void xcd_barrier(const XcdBarrier& b) {
;     ...
;             __builtin_amdgcn_fence(__ATOMIC_ACQUIRE, "agent");
;             xb_add(&bar[XB_XGEN(b.x)], 1u);
.LBB0_1972:
	s_or_b64 exec, exec, s[0:1]
	s_mov_b64 s[0:1], exec
	v_mbcnt_lo_u32_b32 v0, s0, 0
	v_mbcnt_hi_u32_b32 v0, s1, v0
	v_cmp_eq_u32_e32 vcc, 0, v0
	s_waitcnt vmcnt(0)
	s_and_saveexec_b64 s[6:7], vcc
	s_cbranch_execnz .LBB0_1973
	s_getpc_b64 s[98:99]
